# speedup vs baseline: 1.0078x; 1.0017x over previous
; DEV void stage_vt(const u16* __restrict__ g, u16* sVt) {
; #pragma unroll 2
;   for (int c = tidx(); c < 64 * 16; c += NT) {
;     int key = c & 63, dc = (c >> 6) * 8;
;     uint4 v = *(const uint4*)(g + (size_t)key * DIN + dc);
;     u16* d = sVt + dc * VS + key;
;     d[0 * VS] = (u16)(v.x & 0xffff); d[1 * VS] = (u16)(v.x >> 16);
;     d[2 * VS] = (u16)(v.y & 0xffff); d[3 * VS] = (u16)(v.y >> 16);
;     d[4 * VS] = (u16)(v.z & 0xffff); d[5 * VS] = (u16)(v.z >> 16);
;     d[6 * VS] = (u16)(v.w & 0xffff); d[7 * VS] = (u16)(v.w >> 16);
;   }
.LBB0_496:
	v_ashrrev_i32_e32 v49, 3, v47
	v_and_b32_e32 v54, -8, v49
	v_ashrrev_i32_e32 v55, 31, v54
	v_lshl_add_u64 v[50:51], v[54:55], 1, v[36:37]
	global_load_dwordx4 v[200:203], v[50:51], off offset:2048
	v_mul_lo_u32 v49, v54, s30
	v_or_b32_e32 v49, v48, v49
	v_cmp_lt_i32_e32 vcc, -1, v47
	s_or_b64 s[16:17], vcc, s[16:17]
	v_add_u32_e32 v208, 0x200, v47
	v_ashrrev_i32_e32 v208, 3, v208
	v_and_b32_e32 v210, -8, v208
	v_ashrrev_i32_e32 v211, 31, v210
	v_lshl_add_u64 v[212:213], v[210:211], 1, v[36:37]
	global_load_dwordx4 v[204:207], v[212:213], off offset:2048
	v_mul_lo_u32 v208, v210, s30
	v_or_b32_e32 v208, v48, v208
	v_add_u32_e32 v47, 0x400, v47
	s_waitcnt vmcnt(1)
	ds_write_b16 v49, v200 offset:18432
	ds_write_b16_d16_hi v49, v200 offset:18576
	ds_write_b16 v49, v201 offset:18720
	ds_write_b16_d16_hi v49, v201 offset:18864
	ds_write_b16 v49, v202 offset:19008
	ds_write_b16_d16_hi v49, v202 offset:19152
	ds_write_b16 v49, v203 offset:19296
	ds_write_b16_d16_hi v49, v203 offset:19440
	s_waitcnt vmcnt(0)
	ds_write_b16 v208, v204 offset:18432
	ds_write_b16_d16_hi v208, v204 offset:18576
	ds_write_b16 v208, v205 offset:18720
	ds_write_b16_d16_hi v208, v205 offset:18864
	ds_write_b16 v208, v206 offset:19008
	ds_write_b16_d16_hi v208, v206 offset:19152
	ds_write_b16 v208, v207 offset:19296
	ds_write_b16_d16_hi v208, v207 offset:19440
	s_andn2_b64 exec, exec, s[16:17]
	s_cbranch_execnz .LBB0_496

; DEV float bflo(uint32_t w) { return __uint_as_float(w << 16); }
; DEV float bfhi(uint32_t w) { return __uint_as_float(w & 0xffff0000u); }
; DEV void ret_state_item(const Params& p, int item, unsigned char* smem) {
;     ...
;     for (int c = tid; c < 64 * 16; c += NT) {
;       int key = c & 63, dc = (c >> 6) * 8;
;       uint4 v = *(const uint4*)(base + (size_t)(jh * 64 + key) * DIN + C_RK + h * 128 + dc);
;       const float z = __expf(lg * (float)(127 - (jh * 64 + key))) * 0.08838834764831845f;
;       u16* d = sKz + dc * VS + key;
;       d[0 * VS] = f2bf(bflo(v.x) * z); d[1 * VS] = f2bf(bfhi(v.x) * z);
;       d[2 * VS] = f2bf(bflo(v.y) * z); d[3 * VS] = f2bf(bfhi(v.y) * z);
;       d[4 * VS] = f2bf(bflo(v.z) * z); d[5 * VS] = f2bf(bfhi(v.z) * z);
;       d[6 * VS] = f2bf(bflo(v.w) * z); d[7 * VS] = f2bf(bfhi(v.w) * z);
;     }
.LBB0_502:
	v_ashrrev_i32_e32 v49, 3, v48
	v_and_b32_e32 v54, -8, v49
	v_ashrrev_i32_e32 v55, 31, v54
	v_lshl_add_u64 v[50:51], v[54:55], 1, v[36:37]
	global_load_dwordx4 v[200:203], v[50:51], off offset:1024
	v_mul_lo_u32 v49, v54, s30
	v_or_b32_e32 v49, v42, v49
	v_cmp_lt_i32_e32 vcc, -1, v48
	s_or_b64 s[16:17], vcc, s[16:17]
	v_add_u32_e32 v208, 0x200, v48
	v_ashrrev_i32_e32 v208, 3, v208
	v_and_b32_e32 v210, -8, v208
	v_ashrrev_i32_e32 v211, 31, v210
	v_lshl_add_u64 v[212:213], v[210:211], 1, v[36:37]
	global_load_dwordx4 v[204:207], v[212:213], off offset:1024
	v_mul_lo_u32 v208, v210, s30
	v_or_b32_e32 v208, v42, v208
	v_add_u32_e32 v48, 0x400, v48
	s_waitcnt vmcnt(1)
	v_lshlrev_b32_e32 v54, 16, v200
	v_and_b32_e32 v50, 0xffff0000, v200
	v_mul_f32_e32 v50, v47, v50
	v_cvt_pk_bf16_f32 v50, v50, s0
	ds_write_b16 v49, v50 offset:144
	v_lshlrev_b32_e32 v50, 16, v201
	v_mul_f32_e32 v50, v47, v50
	v_cvt_pk_bf16_f32 v50, v50, s0
	ds_write_b16 v49, v50 offset:288
	v_and_b32_e32 v50, 0xffff0000, v201
	v_mul_f32_e32 v50, v47, v50
	v_cvt_pk_bf16_f32 v50, v50, s0
	ds_write_b16 v49, v50 offset:432
	v_lshlrev_b32_e32 v50, 16, v202
	v_mul_f32_e32 v50, v47, v50
	v_cvt_pk_bf16_f32 v50, v50, s0
	ds_write_b16 v49, v50 offset:576
	v_and_b32_e32 v50, 0xffff0000, v202
	v_mul_f32_e32 v50, v47, v50
	v_cvt_pk_bf16_f32 v50, v50, s0
	ds_write_b16 v49, v50 offset:720
	v_lshlrev_b32_e32 v50, 16, v203
	v_mul_f32_e32 v50, v47, v50
	v_cvt_pk_bf16_f32 v50, v50, s0
	ds_write_b16 v49, v50 offset:864
	v_and_b32_e32 v50, 0xffff0000, v203
	v_mul_f32_e32 v54, v47, v54
	v_mul_f32_e32 v50, v47, v50
	v_cvt_pk_bf16_f32 v54, v54, s0
	v_cvt_pk_bf16_f32 v50, v50, s0
	ds_write_b16 v49, v54
	ds_write_b16 v49, v50 offset:1008
	s_waitcnt vmcnt(0)
	v_lshlrev_b32_e32 v54, 16, v204
	v_and_b32_e32 v50, 0xffff0000, v204
	v_mul_f32_e32 v50, v47, v50
	v_cvt_pk_bf16_f32 v50, v50, s0
	ds_write_b16 v208, v50 offset:144
	v_lshlrev_b32_e32 v50, 16, v205
	v_mul_f32_e32 v50, v47, v50
	v_cvt_pk_bf16_f32 v50, v50, s0
	ds_write_b16 v208, v50 offset:288
	v_and_b32_e32 v50, 0xffff0000, v205
	v_mul_f32_e32 v50, v47, v50
	v_cvt_pk_bf16_f32 v50, v50, s0
	ds_write_b16 v208, v50 offset:432
	v_lshlrev_b32_e32 v50, 16, v206
	v_mul_f32_e32 v50, v47, v50
	v_cvt_pk_bf16_f32 v50, v50, s0
	ds_write_b16 v208, v50 offset:576
	v_and_b32_e32 v50, 0xffff0000, v206
	v_mul_f32_e32 v50, v47, v50
	v_cvt_pk_bf16_f32 v50, v50, s0
	ds_write_b16 v208, v50 offset:720
	v_lshlrev_b32_e32 v50, 16, v207
	v_mul_f32_e32 v50, v47, v50
	v_cvt_pk_bf16_f32 v50, v50, s0
	ds_write_b16 v208, v50 offset:864
	v_and_b32_e32 v50, 0xffff0000, v207
	v_mul_f32_e32 v54, v47, v54
	v_mul_f32_e32 v50, v47, v50
	v_cvt_pk_bf16_f32 v54, v54, s0
	v_cvt_pk_bf16_f32 v50, v50, s0
	ds_write_b16 v208, v54
	ds_write_b16 v208, v50 offset:1008
	s_andn2_b64 exec, exec, s[16:17]
	s_cbranch_execnz .LBB0_502
	s_branch .LBB0_490
